# v26 plus P3: state-unit K/V loads and prefix-task decay constant requested ahead of the waits
# speedup vs baseline: 1.0115x; 1.0023x over previous
.LBB0_291:
	s_ashr_i32 s3, s38, 5
	s_bfe_u32 s0, s38, 0x10003
	s_and_b32 s3, s3, 0x3ffffffe
	s_ashr_i32 s1, s38, 4
	s_or_b32 s3, s3, s0
	s_and_b32 s4, s1, 3
	s_lshl_b32 s3, s3, 2
	s_or_b32 s6, s3, s4
	s_ashr_i32 s7, s6, 31
	s_lshl_b64 s[6:7], s[6:7], 16
	s_add_u32 s5, s60, s6
	s_addc_u32 s7, s61, s7
	s_lshl_b32 s3, s38, 4
	s_and_b32 s3, s3, 0x70
	s_lshl_b32 s6, s3, 2
	v_ashrrev_i32_e32 v8, 2, v130
	s_add_u32 s6, s5, s6
	v_lshlrev_b32_e32 v2, 7, v8
	s_addc_u32 s7, s7, 0
	v_ashrrev_i32_e32 v3, 31, v2
	v_and_b32_e32 v4, 12, v141
	v_lshl_add_u64 v[2:3], v[2:3], 2, s[6:7]
	v_lshlrev_b32_e32 v6, 2, v4
	v_mov_b32_e32 v7, 0
	v_lshl_add_u64 v[2:3], v[2:3], 0, v[6:7]
	s_barrier
	global_load_dwordx4 v[2:5], v[2:3], off
	s_lshl_b32 s98, s4, 2
	s_lshl_b32 s99, s0, 4
	s_or_b32 s98, s99, s98
	v_readlane_b32 s100, v242, 4
	v_readlane_b32 s101, v242, 5
	v_mov_b32_e32 v240, s98
	s_nop 4
	global_load_dword v240, v240, s[100:101]
	v_cmp_eq_u32_e32 vcc, 0, v130
	s_and_saveexec_b64 s[6:7], vcc
	s_cbranch_execz .LBB0_306
	s_lshl_b32 s8, s1, 6
	s_ashr_i32 s9, s8, 31
	s_lshl_b64 s[8:9], s[8:9], 2
	s_add_u32 s8, s82, s8
	s_addc_u32 s9, s83, s9
	s_mov_b32 s5, 0x100000
	s_branch .LBB0_295

.LBB0_306:
	s_or_b64 exec, exec, s[6:7]
	s_movk_i32 s5, 0x44
	s_add_u32 s94, s54, 0xa800000
	v_mul_lo_u32 v7, v8, s5
	s_movk_i32 s5, 0x100
	s_addc_u32 s95, s55, 0
	v_add3_u32 v6, 0, v7, v6
	v_cmp_gt_i32_e32 vcc, s5, v130
	s_waitcnt vmcnt(0)
	ds_write2_b32 v6, v2, v3 offset1:1
	ds_write2_b32 v6, v4, v5 offset0:2 offset1:3
	s_waitcnt lgkmcnt(0)
	s_barrier
	s_and_saveexec_b64 s[8:9], vcc
	s_cbranch_execz .LBB0_308
	s_lshl_b32 s4, s4, 2
	s_lshl_b32 s5, s0, 4
	s_or_b32 s4, s5, s4
	v_readlane_b32 s16, v242, 0
	v_mov_b32_e32 v2, s4
	v_readlane_b32 s20, v242, 4
	v_readlane_b32 s21, v242, 5
	s_mov_b32 s6, 0xbfb8aa3b
	v_lshlrev_b32_e32 v3, 3, v130
	s_lshl_b32 s14, s1, 3
	s_lshl_b32 s1, s0, 15
	v_readlane_b32 s17, v242, 1
	v_mov_b32_e32 v8, v240
	v_add_lshl_u32 v2, v1, s3, 7
	v_readlane_b32 s18, v242, 2
	v_and_b32_e32 v11, 0x78, v3
	v_ashrrev_i32_e32 v3, 31, v2
	s_add_u32 s16, s92, s1
	v_readlane_b32 s19, v242, 3
	v_lshlrev_b64 v[36:37], 1, v[2:3]
	s_addc_u32 s17, s93, 0
	s_or_b32 s18, s14, 6
	s_or_b32 s20, s14, 7
	v_mov_b32_e32 v19, 0
	v_lshlrev_b32_e32 v18, 1, v11
	s_ashr_i32 s15, s14, 31
	v_lshl_add_u64 v[2:3], s[16:17], 0, v[36:37]
	s_ashr_i32 s19, s18, 31
	s_ashr_i32 s21, s20, 31
	s_lshl_b64 s[16:17], s[14:15], 16
	v_lshl_add_u64 v[14:15], v[2:3], 0, v[18:19]
	s_lshl_b64 s[18:19], s[18:19], 16
	s_lshl_b64 s[20:21], s[20:21], 16
	s_mov_b32 s5, 0x42ce8ed0
	v_lshl_add_u64 v[2:3], v[14:15], 0, s[16:17]
	v_lshl_add_u64 v[4:5], v[14:15], 0, s[18:19]
	v_lshl_add_u64 v[6:7], v[14:15], 0, s[20:21]
	s_mov_b32 s7, 0xc2b17218
	global_load_dwordx4 v[20:23], v[2:3], off
	s_nop 0
	global_load_dwordx4 v[2:5], v[4:5], off
	s_nop 0
	global_load_dwordx4 v[24:27], v[6:7], off
	v_mov_b32_e32 v9, 0x7f800000
	s_mov_b32 s10, 0x3f2aaaab
	s_mov_b32 s11, 0x3f317218
	v_mov_b32_e32 v10, 0x3ecc95a3
	s_mov_b32 s4, 0x7f800000
	s_mov_b32 s3, 0x33800000
	v_lshlrev_b32_e32 v1, 2, v1
	v_readlane_b32 s22, v242, 6
	v_readlane_b32 s23, v242, 7
	v_readlane_b32 s24, v242, 8
	v_readlane_b32 s25, v242, 9
	v_readlane_b32 s26, v242, 10
	v_readlane_b32 s27, v242, 11
	v_readlane_b32 s28, v242, 12
	v_readlane_b32 s29, v242, 13
	v_readlane_b32 s30, v242, 14
	v_readlane_b32 s31, v242, 15
	s_waitcnt vmcnt(3)
	v_mul_f32_e32 v12, 0xbfb8aa3b, v8
	v_fma_f32 v13, v8, s6, -v12
	v_rndne_f32_e32 v16, v12
	v_fmamk_f32 v13, v8, 0xb2a5705f, v13
	v_sub_f32_e32 v12, v12, v16
	v_add_f32_e32 v12, v12, v13
	v_cvt_i32_f32_e32 v16, v16
	v_exp_f32_e32 v12, v12
	v_cmp_nlt_f32_e32 vcc, s5, v8
	v_ldexp_f32 v6, v12, v16
	s_nop 0
	v_cndmask_b32_e32 v6, 0, v6, vcc
	v_cmp_ngt_f32_e32 vcc, s7, v8
	s_nop 1
	v_cndmask_b32_e32 v8, v9, v6, vcc
	v_add_f32_e32 v12, 1.0, v8
	v_add_f32_e32 v13, -1.0, v12
	v_frexp_mant_f32_e32 v16, v12
	v_cvt_f64_f32_e32 v[6:7], v12
	v_sub_f32_e32 v17, v13, v12
	v_frexp_exp_i32_f64_e32 v6, v[6:7]
	v_cmp_gt_f32_e32 vcc, s10, v16
	v_sub_f32_e32 v13, v8, v13
	v_add_f32_e32 v7, 1.0, v17
	v_subbrev_co_u32_e32 v6, vcc, 0, v6, vcc
	v_add_f32_e32 v7, v13, v7
	v_sub_u32_e32 v13, 0, v6
	v_cvt_f32_i32_e32 v6, v6
	v_ldexp_f32 v12, v12, v13
	v_ldexp_f32 v7, v7, v13
	v_add_f32_e32 v13, -1.0, v12
	v_add_f32_e32 v16, 1.0, v12
	v_add_f32_e32 v17, 1.0, v13
	v_add_f32_e32 v28, -1.0, v16
	v_sub_f32_e32 v17, v12, v17
	v_sub_f32_e32 v12, v12, v28
	v_mul_f32_e32 v28, 0x3f317218, v6
	v_add_f32_e32 v17, v7, v17
	v_add_f32_e32 v7, v7, v12
	v_fma_f32 v12, v6, s11, -v28
	v_add_f32_e32 v29, v13, v17
	v_add_f32_e32 v30, v16, v7
	v_fmamk_f32 v6, v6, 0xb102e308, v12
	v_sub_f32_e32 v12, v13, v29
	v_sub_f32_e32 v13, v16, v30
	v_rcp_f32_e32 v16, v30
	v_add_f32_e32 v31, v28, v6
	v_add_f32_e32 v7, v7, v13
	v_sub_f32_e32 v13, v31, v28
	v_sub_f32_e32 v6, v6, v13
	v_mul_f32_e32 v13, v29, v16
	v_add_f32_e32 v12, v17, v12
	v_mul_f32_e32 v17, v30, v13
	v_fma_f32 v28, v13, v30, -v17
	v_fmac_f32_e32 v28, v13, v7
	v_add_f32_e32 v32, v17, v28
	v_sub_f32_e32 v33, v29, v32
	v_sub_f32_e32 v17, v32, v17
	v_sub_f32_e32 v29, v29, v33
	v_sub_f32_e32 v17, v17, v28
	v_sub_f32_e32 v28, v29, v32
	v_add_f32_e32 v12, v12, v28
	v_add_f32_e32 v12, v17, v12
	v_add_f32_e32 v17, v33, v12
	v_mul_f32_e32 v28, v16, v17
	v_sub_f32_e32 v29, v33, v17
	v_mul_f32_e32 v32, v30, v28
	v_add_f32_e32 v12, v12, v29
	v_add_f32_e32 v29, v13, v28
	v_fma_f32 v30, v28, v30, -v32
	v_sub_f32_e32 v13, v29, v13
	v_fmac_f32_e32 v30, v28, v7
	v_sub_f32_e32 v7, v28, v13
	v_add_f32_e32 v13, v32, v30
	v_sub_f32_e32 v28, v13, v32
	v_sub_f32_e32 v32, v17, v13
	v_sub_f32_e32 v17, v17, v32
	v_sub_f32_e32 v13, v17, v13
	v_sub_f32_e32 v28, v28, v30
	v_add_f32_e32 v12, v12, v13
	v_add_f32_e32 v12, v28, v12
	v_add_f32_e32 v12, v32, v12
	v_mul_f32_e32 v12, v16, v12
	v_add_f32_e32 v7, v7, v12
	v_add_f32_e32 v12, v29, v7
	v_mul_f32_e32 v13, v12, v12
	v_fmac_f32_e32 v10, 0x3e9b6dac, v13
	v_sub_f32_e32 v16, v12, v29
	v_ldexp_f32 v17, v12, 1
	v_mul_f32_e32 v12, v12, v13
	v_fmaak_f32 v10, v13, v10, 0x3f2aaada
	v_mul_f32_e32 v10, v12, v10
	v_add_f32_e32 v12, v17, v10
	v_sub_f32_e32 v7, v7, v16
	v_sub_f32_e32 v13, v12, v17
	v_ldexp_f32 v7, v7, 1
	v_sub_f32_e32 v10, v10, v13
	v_add_f32_e32 v7, v7, v10
	v_add_f32_e32 v10, v12, v7
	v_sub_f32_e32 v12, v10, v12
	v_add_f32_e32 v13, v31, v10
	v_sub_f32_e32 v7, v7, v12
	v_sub_f32_e32 v12, v13, v31
	v_sub_f32_e32 v16, v13, v12
	v_sub_f32_e32 v10, v10, v12
	v_add_f32_e32 v12, v6, v7
	v_sub_f32_e32 v16, v31, v16
	v_sub_f32_e32 v17, v12, v6
	v_add_f32_e32 v10, v10, v16
	v_sub_f32_e32 v16, v12, v17
	v_sub_f32_e32 v6, v6, v16
	v_sub_f32_e32 v7, v7, v17
	v_add_f32_e32 v6, v7, v6
	v_add_f32_e32 v7, v12, v10
	v_add_f32_e32 v10, v13, v7
	v_sub_f32_e32 v12, v10, v13
	v_sub_f32_e32 v7, v7, v12
	v_add_f32_e32 v6, v6, v7
	v_add_f32_e32 v6, v10, v6
	v_cmp_neq_f32_e32 vcc, s4, v8
	s_or_b32 s4, s14, 1
	s_ashr_i32 s5, s4, 31
	v_cndmask_b32_e32 v6, v9, v6, vcc
	v_cmp_lt_f32_e64 vcc, |v8|, s3
	s_lshl_b64 s[4:5], s[4:5], 16
	s_nop 0
	v_cndmask_b32_e32 v6, v6, v8, vcc
	v_mul_f32_e32 v6, 0xbfb8aa3b, v6
	v_mul_f32_e32 v10, 0x43800000, v6
	v_lshl_add_u64 v[6:7], v[14:15], 0, s[4:5]
	s_or_b32 s4, s14, 2
	s_ashr_i32 s5, s4, 31
	v_exp_f32_e32 v50, v10
	v_mul_u32_u24_e32 v10, 0x44, v11
	s_lshl_b64 s[4:5], s[4:5], 16
	v_add3_u32 v1, 0, v1, v10
	v_lshl_add_u64 v[10:11], v[14:15], 0, s[4:5]
	s_or_b32 s4, s14, 3
	global_load_dwordx4 v[6:9], v[6:7], off
	s_ashr_i32 s5, s4, 31
	s_lshl_b64 s[4:5], s[4:5], 16
	v_lshl_add_u64 v[16:17], v[14:15], 0, s[4:5]
	s_or_b32 s4, s14, 4
	s_ashr_i32 s5, s4, 31
	s_lshl_b64 s[4:5], s[4:5], 16
	ds_read2_b32 v[40:41], v1 offset1:17
	ds_read2_b32 v[42:43], v1 offset0:34 offset1:51
	ds_read2_b32 v[44:45], v1 offset0:68 offset1:85
	ds_read2_b32 v[46:47], v1 offset0:102 offset1:119
	global_load_dwordx4 v[10:13], v[10:11], off
	s_nop 0
	global_load_dwordx4 v[28:31], v[16:17], off
	v_lshl_add_u64 v[16:17], v[14:15], 0, s[4:5]
	s_or_b32 s4, s14, 5
	s_ashr_i32 s5, s4, 31
	s_lshl_b64 s[4:5], s[4:5], 16
	v_lshl_add_u64 v[14:15], v[14:15], 0, s[4:5]
	global_load_dwordx4 v[32:35], v[16:17], off
	s_nop 0
	global_load_dwordx4 v[14:17], v[14:15], off
	s_add_u32 s4, s94, s1
	s_addc_u32 s5, s95, 0
	s_cmp_eq_u32 s0, 0
	s_cselect_b64 vcc, -1, 0
	v_lshl_add_u64 v[36:37], s[4:5], 0, v[36:37]
	s_and_b64 s[4:5], vcc, exec
	s_cselect_b32 s5, 0, 7
	s_cselect_b32 s10, 1, 6
	s_cselect_b32 s11, 2, 5
	s_cselect_b32 s4, 5, 2
	s_cselect_b32 s3, 6, 1
	s_cselect_b32 s1, 7, 0
	s_or_b32 s6, s5, s14
	s_ashr_i32 s7, s6, 31
	v_lshl_add_u64 v[18:19], v[36:37], 0, v[18:19]
	s_lshl_b64 s[6:7], s[6:7], 16
	v_lshl_add_u64 v[48:49], v[18:19], 0, s[6:7]
	s_waitcnt vmcnt(5)
	v_cndmask_b32_e32 v20, v24, v20, vcc
	s_or_b32 s6, s10, s14
	v_cndmask_b32_e32 v1, v27, v23, vcc
	v_cndmask_b32_e32 v22, v26, v22, vcc
	v_lshlrev_b32_e32 v26, 16, v20
	s_ashr_i32 s7, s6, 31
	s_waitcnt lgkmcnt(3)
	v_cvt_pk_bf16_f32 v36, v40, v41
	s_waitcnt lgkmcnt(2)
	v_cvt_pk_bf16_f32 v37, v42, v43
	s_waitcnt lgkmcnt(1)
	v_cvt_pk_bf16_f32 v38, v44, v45
	s_waitcnt lgkmcnt(0)
	v_cvt_pk_bf16_f32 v39, v46, v47
	v_cndmask_b32_e32 v21, v25, v21, vcc
	v_fmac_f32_e32 v26, v50, v40
	v_lshlrev_b32_e32 v40, 16, v1
	v_and_b32_e32 v1, 0xffff0000, v1
	s_lshl_b64 s[6:7], s[6:7], 16
	global_store_dwordx4 v[48:49], v[36:39], off
	v_and_b32_e32 v27, 0xffff0000, v20
	v_fmac_f32_e32 v40, v50, v46
	v_lshlrev_b32_e32 v36, 16, v21
	v_and_b32_e32 v37, 0xffff0000, v21
	v_lshlrev_b32_e32 v38, 16, v22
	v_and_b32_e32 v39, 0xffff0000, v22
	v_fmac_f32_e32 v1, v50, v47
	v_cvt_pk_bf16_f32 v23, v40, v1
	v_lshl_add_u64 v[24:25], v[18:19], 0, s[6:7]
	v_fmac_f32_e32 v27, v50, v41
	v_fmac_f32_e32 v36, v50, v42
	v_fmac_f32_e32 v37, v50, v43
	v_fmac_f32_e32 v38, v50, v44
	v_fmac_f32_e32 v39, v50, v45
	v_cvt_pk_bf16_f32 v20, v26, v27
	v_cvt_pk_bf16_f32 v21, v36, v37
	v_cvt_pk_bf16_f32 v22, v38, v39
	global_store_dwordx4 v[24:25], v[20:23], off
	s_or_b32 s6, s11, s14
	s_ashr_i32 s7, s6, 31
	s_lshl_b64 s[6:7], s[6:7], 16
	v_lshl_add_u64 v[24:25], v[18:19], 0, s[6:7]
	s_or_b32 s5, s0, s14
	s_add_i32 s6, s5, 3
	s_ashr_i32 s7, s6, 31
	s_lshl_b64 s[6:7], s[6:7], 16
	s_or_b32 s4, s4, s14
	s_ashr_i32 s5, s4, 31
	s_lshl_b64 s[4:5], s[4:5], 16
	s_waitcnt vmcnt(6)
	v_cndmask_b32_e32 v23, v2, v6, vcc
	v_lshlrev_b32_e32 v41, 16, v23
	v_cndmask_b32_e32 v22, v3, v7, vcc
	v_fmac_f32_e32 v41, v50, v26
	v_and_b32_e32 v26, 0xffff0000, v23
	v_fmac_f32_e32 v26, v50, v27
	v_lshlrev_b32_e32 v27, 16, v22
	v_cndmask_b32_e32 v21, v4, v8, vcc
	v_fmac_f32_e32 v27, v50, v36
	v_and_b32_e32 v36, 0xffff0000, v22
	v_fmac_f32_e32 v36, v50, v37
	v_lshlrev_b32_e32 v37, 16, v21
	v_cndmask_b32_e32 v20, v5, v9, vcc
	v_fmac_f32_e32 v37, v50, v38
	v_and_b32_e32 v38, 0xffff0000, v21
	v_fmac_f32_e32 v38, v50, v39
	v_lshlrev_b32_e32 v39, 16, v20
	v_fmac_f32_e32 v39, v50, v40
	v_and_b32_e32 v40, 0xffff0000, v20
	v_cvt_pk_bf16_f32 v22, v37, v38
	v_fmac_f32_e32 v40, v50, v1
	v_cvt_pk_bf16_f32 v20, v41, v26
	v_cvt_pk_bf16_f32 v21, v27, v36
	v_cvt_pk_bf16_f32 v23, v39, v40
	global_store_dwordx4 v[24:25], v[20:23], off
	s_waitcnt vmcnt(3)
	v_cndmask_b32_e32 v1, v17, v13, vcc
	v_lshl_add_u64 v[24:25], v[18:19], 0, s[6:7]
	v_cndmask_b32_e32 v22, v14, v10, vcc
	v_lshlrev_b32_e32 v42, 16, v22
	v_cndmask_b32_e32 v21, v15, v11, vcc
	v_fmac_f32_e32 v42, v50, v41
	v_and_b32_e32 v41, 0xffff0000, v22
	v_fmac_f32_e32 v41, v50, v26
	v_lshlrev_b32_e32 v26, 16, v21
	v_cndmask_b32_e32 v20, v16, v12, vcc
	v_fmac_f32_e32 v26, v50, v27
	v_and_b32_e32 v27, 0xffff0000, v21
	v_fmac_f32_e32 v27, v50, v36
	v_lshlrev_b32_e32 v36, 16, v20
	v_fmac_f32_e32 v36, v50, v37
	v_and_b32_e32 v37, 0xffff0000, v20
	v_fmac_f32_e32 v37, v50, v38
	v_lshlrev_b32_e32 v38, 16, v1
	v_and_b32_e32 v1, 0xffff0000, v1
	v_fmac_f32_e32 v38, v50, v39
	v_fmac_f32_e32 v1, v50, v40
	v_cvt_pk_bf16_f32 v23, v38, v1
	v_cvt_pk_bf16_f32 v20, v42, v41
	v_cvt_pk_bf16_f32 v21, v26, v27
	v_cvt_pk_bf16_f32 v22, v36, v37
	global_store_dwordx4 v[24:25], v[20:23], off
	s_sub_i32 s6, s14, s0
	s_ashr_i32 s7, s6, 31
	v_cndmask_b32_e32 v23, v32, v28, vcc
	v_cndmask_b32_e32 v22, v33, v29, vcc
	v_and_b32_e32 v40, 0xffff0000, v23
	v_fmac_f32_e32 v40, v50, v41
	v_lshlrev_b32_e32 v41, 16, v22
	v_cndmask_b32_e32 v21, v34, v30, vcc
	v_fmac_f32_e32 v41, v50, v26
	v_and_b32_e32 v26, 0xffff0000, v22
	v_fmac_f32_e32 v26, v50, v27
	v_lshlrev_b32_e32 v27, 16, v21
	s_lshl_b64 s[6:7], s[6:7], 16
	v_cndmask_b32_e32 v20, v35, v31, vcc
	v_fmac_f32_e32 v27, v50, v36
	v_and_b32_e32 v36, 0xffff0000, v21
	v_lshl_add_u64 v[24:25], v[18:19], 0, s[6:7]
	s_mov_b32 s0, 0x40000
	v_fmac_f32_e32 v36, v50, v37
	v_lshlrev_b32_e32 v37, 16, v20
	v_add_co_u32_e64 v24, s[6:7], s0, v24
	v_lshlrev_b32_e32 v39, 16, v23
	v_fmac_f32_e32 v37, v50, v38
	v_and_b32_e32 v38, 0xffff0000, v20
	v_cvt_pk_bf16_f32 v21, v41, v26
	v_addc_co_u32_e64 v25, s[6:7], 0, v25, s[6:7]
	v_fmac_f32_e32 v39, v50, v42
	v_fmac_f32_e32 v38, v50, v1
	v_cvt_pk_bf16_f32 v20, v39, v40
	v_cvt_pk_bf16_f32 v22, v27, v36
	v_cvt_pk_bf16_f32 v23, v37, v38
	global_store_dwordx4 v[24:25], v[20:23], off
	v_cndmask_b32_e32 v1, v31, v35, vcc
	v_lshl_add_u64 v[24:25], v[18:19], 0, s[4:5]
	v_cndmask_b32_e32 v21, v29, v33, vcc
	v_cndmask_b32_e32 v20, v30, v34, vcc
	v_and_b32_e32 v31, 0xffff0000, v21
	v_cndmask_b32_e32 v22, v28, v32, vcc
	v_fmac_f32_e32 v31, v50, v26
	v_lshlrev_b32_e32 v26, 16, v20
	v_lshlrev_b32_e32 v28, 16, v22
	v_and_b32_e32 v29, 0xffff0000, v22
	v_lshlrev_b32_e32 v30, 16, v21
	v_fmac_f32_e32 v26, v50, v27
	v_and_b32_e32 v27, 0xffff0000, v20
	v_lshlrev_b32_e32 v32, 16, v1
	v_and_b32_e32 v1, 0xffff0000, v1
	v_fmac_f32_e32 v28, v50, v39
	v_fmac_f32_e32 v29, v50, v40
	v_fmac_f32_e32 v30, v50, v41
	v_fmac_f32_e32 v27, v50, v36
	v_fmac_f32_e32 v32, v50, v37
	v_fmac_f32_e32 v1, v50, v38
	v_cvt_pk_bf16_f32 v20, v28, v29
	v_cvt_pk_bf16_f32 v21, v30, v31
	v_cvt_pk_bf16_f32 v22, v26, v27
	v_cvt_pk_bf16_f32 v23, v32, v1
	v_cndmask_b32_e32 v12, v12, v16, vcc
	v_cndmask_b32_e32 v11, v11, v15, vcc
	global_store_dwordx4 v[24:25], v[20:23], off
	v_cndmask_b32_e32 v13, v13, v17, vcc
	v_cndmask_b32_e32 v10, v10, v14, vcc
	v_lshlrev_b32_e32 v20, 16, v11
	v_and_b32_e32 v21, 0xffff0000, v11
	v_lshlrev_b32_e32 v22, 16, v12
	v_and_b32_e32 v23, 0xffff0000, v12
	s_or_b32 s4, s3, s14
	v_cndmask_b32_e32 v4, v8, v4, vcc
	v_cndmask_b32_e32 v3, v7, v3, vcc
	s_or_b32 s0, s1, s14
	v_lshlrev_b32_e32 v16, 16, v10
	v_and_b32_e32 v17, 0xffff0000, v10
	v_fmac_f32_e32 v20, v50, v30
	v_fmac_f32_e32 v21, v50, v31
	v_fmac_f32_e32 v22, v50, v26
	v_fmac_f32_e32 v23, v50, v27
	v_and_b32_e32 v25, 0xffff0000, v13
	s_ashr_i32 s5, s4, 31
	v_cndmask_b32_e32 v2, v6, v2, vcc
	v_lshlrev_b32_e32 v6, 16, v3
	v_and_b32_e32 v3, 0xffff0000, v3
	v_lshlrev_b32_e32 v7, 16, v4
	v_and_b32_e32 v4, 0xffff0000, v4
	s_ashr_i32 s1, s0, 31
	v_fmac_f32_e32 v16, v50, v28
	v_fmac_f32_e32 v17, v50, v29
	v_lshlrev_b32_e32 v24, 16, v13
	v_fmac_f32_e32 v25, v50, v1
	s_lshl_b64 s[4:5], s[4:5], 16
	v_cndmask_b32_e32 v1, v9, v5, vcc
	v_lshlrev_b32_e32 v5, 16, v2
	v_and_b32_e32 v2, 0xffff0000, v2
	v_fmac_f32_e32 v6, v50, v20
	v_fmac_f32_e32 v3, v50, v21
	v_fmac_f32_e32 v7, v50, v22
	v_fmac_f32_e32 v4, v50, v23
	s_lshl_b64 s[0:1], s[0:1], 16
	v_fmac_f32_e32 v24, v50, v32
	v_lshl_add_u64 v[14:15], v[18:19], 0, s[4:5]
	v_fmac_f32_e32 v5, v50, v16
	v_fmac_f32_e32 v2, v50, v17
	v_lshlrev_b32_e32 v8, 16, v1
	v_and_b32_e32 v1, 0xffff0000, v1
	v_cvt_pk_bf16_f32 v3, v6, v3
	v_cvt_pk_bf16_f32 v4, v7, v4
	v_lshl_add_u64 v[6:7], v[18:19], 0, s[0:1]
	v_cvt_pk_bf16_f32 v10, v16, v17
	v_cvt_pk_bf16_f32 v11, v20, v21
	v_cvt_pk_bf16_f32 v12, v22, v23
	v_cvt_pk_bf16_f32 v13, v24, v25
	global_store_dwordx4 v[14:15], v[10:13], off
	v_fmac_f32_e32 v8, v50, v24
	v_fmac_f32_e32 v1, v50, v25
	v_cvt_pk_bf16_f32 v2, v5, v2
	v_cvt_pk_bf16_f32 v5, v8, v1
	global_store_dwordx4 v[6:7], v[2:5], off
